# scan compute: joint two-row DPP reduction and cheaper partial exchange
# baseline (speedup 1.0000x reference)
.Lsc_chunk:
	s_and_b32 s1, s0, 1
	s_lshl_b32 s2, s1, 12
	s_mulk_i32 s1, 0x6080
	s_add_i32 s1, s1, s3
	v_add_u32_e32 v10, s1, v46
	v_add_u32_e32 v11, s1, v47
	v_add_u32_e32 v13, s2, v48
	s_add_i32 s1, s1, 0x6000
	v_mov_b32_e32 v12, s1
	ds_read_b128 v[52:55], v10 offset:0
	ds_read_b64 v[72:73], v11 offset:0
	ds_read_b128 v[64:67], v10 offset:12288
	ds_read_b128 v[60:63], v10 offset:8192
	ds_read_b128 v[56:59], v10 offset:4096
	ds_read_b64 v[74:75], v12 offset:0
	ds_read_b128 v[68:71], v10 offset:16384
	ds_read_b128 v[76:79], v10 offset:256
	ds_read_b64 v[96:97], v11 offset:256
	ds_read_b128 v[88:91], v10 offset:12544
	ds_read_b128 v[84:87], v10 offset:8448
	ds_read_b128 v[80:83], v10 offset:4352
	ds_read_b64 v[98:99], v12 offset:8
	ds_read_b128 v[92:95], v10 offset:16640
	s_waitcnt lgkmcnt(7)
	ds_read_b128 v[100:103], v10 offset:512
	ds_read_b64 v[120:121], v11 offset:512
	ds_read_b128 v[112:115], v10 offset:12800
	ds_read_b128 v[108:111], v10 offset:8704
	ds_read_b128 v[104:107], v10 offset:4608
	ds_read_b64 v[122:123], v12 offset:16
	ds_read_b128 v[116:119], v10 offset:16896
	v_pk_mul_f32 v[16:17], v[0:1], v[52:53]
	v_pk_mul_f32 v[18:19], v[4:5], v[52:53]
	v_pk_mul_f32 v[14:15], v[72:73], s[4:5] op_sel_hi:[1,0]
	v_pk_fma_f32 v[16:17], v[2:3], v[54:55], v[16:17]
	v_pk_fma_f32 v[18:19], v[6:7], v[54:55], v[18:19]
	v_pk_mul_f32 v[20:21], v[64:65], v[14:15] op_sel_hi:[1,0]
	v_pk_mul_f32 v[22:23], v[66:67], v[14:15] op_sel_hi:[1,0]
	v_add_f32_e32 v32, v16, v17
	v_add_f32_e32 v33, v18, v19
	v_pk_mul_f32 v[24:25], v[64:65], v[14:15] op_sel:[0,1] op_sel_hi:[1,1]
	v_pk_mul_f32 v[26:27], v[66:67], v[14:15] op_sel:[0,1] op_sel_hi:[1,1]
	v_cndmask_b32_e64 v34, v32, v33, s[6:7]
	v_cndmask_b32_e64 v35, v33, v32, s[6:7]
	v_pk_mul_f32 v[38:39], v[14:15], v[74:75] op_sel:[0,1] op_sel_hi:[1,1]
	v_pk_fma_f32 v[20:21], v[60:61], v[8:9], v[20:21] op_sel_hi:[1,0,1]
	v_add_f32_dpp v35, v34, v35 row_ror:8 row_mask:0xf bank_mask:0xf bound_ctrl:1
	v_pk_fma_f32 v[22:23], v[62:63], v[8:9], v[22:23] op_sel_hi:[1,0,1]
	v_pk_fma_f32 v[24:25], v[60:61], v[8:9], v[24:25] op_sel:[0,1,0] op_sel_hi:[1,1,1]
	v_pk_fma_f32 v[26:27], v[62:63], v[8:9], v[26:27] op_sel:[0,1,0] op_sel_hi:[1,1,1]
	v_add_f32_dpp v35, v35, v35 quad_perm:[1,0,3,2] row_mask:0xf bank_mask:0xf bound_ctrl:1
	v_pk_fma_f32 v[0:1], v[0:1], v[56:57], v[20:21]
	v_pk_fma_f32 v[2:3], v[2:3], v[58:59], v[22:23]
	v_pk_fma_f32 v[4:5], v[4:5], v[56:57], v[24:25]
	v_add_f32_dpp v35, v35, v35 quad_perm:[2,3,0,1] row_mask:0xf bank_mask:0xf bound_ctrl:1
	v_pk_fma_f32 v[6:7], v[6:7], v[58:59], v[26:27]
	v_pk_mul_f32 v[28:29], v[0:1], v[68:69]
	v_pk_fma_f32 v[38:39], v[8:9], v[74:75], v[38:39] op_sel_hi:[1,0,1]
	v_add_f32_dpp v35, v35, v35 row_half_mirror row_mask:0xf bank_mask:0xf bound_ctrl:1
	v_pk_mul_f32 v[30:31], v[4:5], v[68:69]
	v_pk_fma_f32 v[28:29], v[2:3], v[70:71], v[28:29]
	v_pk_fma_f32 v[30:31], v[6:7], v[70:71], v[30:31]
	v_mov_b32_dpp v34, v35 row_ror:8 row_mask:0xf bank_mask:0xf
	v_add_f32_e32 v16, v28, v29
	v_add_f32_e32 v17, v30, v31
	v_cndmask_b32_e64 v32, v34, v35, s[6:7]
	v_cndmask_b32_e64 v33, v35, v34, s[6:7]
	v_cndmask_b32_e64 v18, v16, v17, s[6:7]
	v_cndmask_b32_e64 v19, v17, v16, s[6:7]
	v_pk_add_f32 v[8:9], v[32:33], v[38:39] neg_lo:[1,1] neg_hi:[1,1]
	s_nop 0
	v_add_f32_dpp v36, v18, v19 row_ror:8 row_mask:0xf bank_mask:0xf bound_ctrl:1
	ds_write_b32 v13, v36 offset:0
	s_waitcnt lgkmcnt(8)
	ds_read_b128 v[52:55], v10 offset:768
	ds_read_b64 v[72:73], v11 offset:768
	ds_read_b128 v[64:67], v10 offset:13056
	ds_read_b128 v[60:63], v10 offset:8960
	ds_read_b128 v[56:59], v10 offset:4864
	ds_read_b64 v[74:75], v12 offset:24
	ds_read_b128 v[68:71], v10 offset:17152
	v_pk_mul_f32 v[16:17], v[0:1], v[76:77]
	v_pk_mul_f32 v[18:19], v[4:5], v[76:77]
	v_pk_mul_f32 v[14:15], v[96:97], s[4:5] op_sel_hi:[1,0]
	v_pk_fma_f32 v[16:17], v[2:3], v[78:79], v[16:17]
	v_pk_fma_f32 v[18:19], v[6:7], v[78:79], v[18:19]
	v_pk_mul_f32 v[20:21], v[88:89], v[14:15] op_sel_hi:[1,0]
	v_pk_mul_f32 v[22:23], v[90:91], v[14:15] op_sel_hi:[1,0]
	v_add_f32_e32 v32, v16, v17
	v_add_f32_e32 v33, v18, v19
	v_pk_mul_f32 v[24:25], v[88:89], v[14:15] op_sel:[0,1] op_sel_hi:[1,1]
	v_pk_mul_f32 v[26:27], v[90:91], v[14:15] op_sel:[0,1] op_sel_hi:[1,1]
	v_cndmask_b32_e64 v34, v32, v33, s[6:7]
	v_cndmask_b32_e64 v35, v33, v32, s[6:7]
	v_pk_mul_f32 v[38:39], v[14:15], v[98:99] op_sel:[0,1] op_sel_hi:[1,1]
	v_pk_fma_f32 v[20:21], v[84:85], v[8:9], v[20:21] op_sel_hi:[1,0,1]
	v_add_f32_dpp v35, v34, v35 row_ror:8 row_mask:0xf bank_mask:0xf bound_ctrl:1
	v_pk_fma_f32 v[22:23], v[86:87], v[8:9], v[22:23] op_sel_hi:[1,0,1]
	v_pk_fma_f32 v[24:25], v[84:85], v[8:9], v[24:25] op_sel:[0,1,0] op_sel_hi:[1,1,1]
	v_pk_fma_f32 v[26:27], v[86:87], v[8:9], v[26:27] op_sel:[0,1,0] op_sel_hi:[1,1,1]
	v_add_f32_dpp v35, v35, v35 quad_perm:[1,0,3,2] row_mask:0xf bank_mask:0xf bound_ctrl:1
	v_pk_fma_f32 v[0:1], v[0:1], v[80:81], v[20:21]
	v_pk_fma_f32 v[2:3], v[2:3], v[82:83], v[22:23]
	v_pk_fma_f32 v[4:5], v[4:5], v[80:81], v[24:25]
	v_add_f32_dpp v35, v35, v35 quad_perm:[2,3,0,1] row_mask:0xf bank_mask:0xf bound_ctrl:1
	v_pk_fma_f32 v[6:7], v[6:7], v[82:83], v[26:27]
	v_pk_mul_f32 v[28:29], v[0:1], v[92:93]
	v_pk_fma_f32 v[38:39], v[8:9], v[98:99], v[38:39] op_sel_hi:[1,0,1]
	v_add_f32_dpp v35, v35, v35 row_half_mirror row_mask:0xf bank_mask:0xf bound_ctrl:1
	v_pk_mul_f32 v[30:31], v[4:5], v[92:93]
	v_pk_fma_f32 v[28:29], v[2:3], v[94:95], v[28:29]
	v_pk_fma_f32 v[30:31], v[6:7], v[94:95], v[30:31]
	v_mov_b32_dpp v34, v35 row_ror:8 row_mask:0xf bank_mask:0xf
	v_add_f32_e32 v16, v28, v29
	v_add_f32_e32 v17, v30, v31
	v_cndmask_b32_e64 v32, v34, v35, s[6:7]
	v_cndmask_b32_e64 v33, v35, v34, s[6:7]
	v_cndmask_b32_e64 v18, v16, v17, s[6:7]
	v_cndmask_b32_e64 v19, v17, v16, s[6:7]
	v_pk_add_f32 v[8:9], v[32:33], v[38:39] neg_lo:[1,1] neg_hi:[1,1]
	s_nop 0
	v_add_f32_dpp v36, v18, v19 row_ror:8 row_mask:0xf bank_mask:0xf bound_ctrl:1
	ds_write_b32 v13, v36 offset:256
	s_waitcnt lgkmcnt(9)
	ds_read_b128 v[76:79], v10 offset:1024
	ds_read_b64 v[96:97], v11 offset:1024
	ds_read_b128 v[88:91], v10 offset:13312
	ds_read_b128 v[84:87], v10 offset:9216
	ds_read_b128 v[80:83], v10 offset:5120
	ds_read_b64 v[98:99], v12 offset:32
	ds_read_b128 v[92:95], v10 offset:17408
	v_pk_mul_f32 v[16:17], v[0:1], v[100:101]
	v_pk_mul_f32 v[18:19], v[4:5], v[100:101]
	v_pk_mul_f32 v[14:15], v[120:121], s[4:5] op_sel_hi:[1,0]
	v_pk_fma_f32 v[16:17], v[2:3], v[102:103], v[16:17]
	v_pk_fma_f32 v[18:19], v[6:7], v[102:103], v[18:19]
	v_pk_mul_f32 v[20:21], v[112:113], v[14:15] op_sel_hi:[1,0]
	v_pk_mul_f32 v[22:23], v[114:115], v[14:15] op_sel_hi:[1,0]
	v_add_f32_e32 v32, v16, v17
	v_add_f32_e32 v33, v18, v19
	v_pk_mul_f32 v[24:25], v[112:113], v[14:15] op_sel:[0,1] op_sel_hi:[1,1]
	v_pk_mul_f32 v[26:27], v[114:115], v[14:15] op_sel:[0,1] op_sel_hi:[1,1]
	v_cndmask_b32_e64 v34, v32, v33, s[6:7]
	v_cndmask_b32_e64 v35, v33, v32, s[6:7]
	v_pk_mul_f32 v[38:39], v[14:15], v[122:123] op_sel:[0,1] op_sel_hi:[1,1]
	v_pk_fma_f32 v[20:21], v[108:109], v[8:9], v[20:21] op_sel_hi:[1,0,1]
	v_add_f32_dpp v35, v34, v35 row_ror:8 row_mask:0xf bank_mask:0xf bound_ctrl:1
	v_pk_fma_f32 v[22:23], v[110:111], v[8:9], v[22:23] op_sel_hi:[1,0,1]
	v_pk_fma_f32 v[24:25], v[108:109], v[8:9], v[24:25] op_sel:[0,1,0] op_sel_hi:[1,1,1]
	v_pk_fma_f32 v[26:27], v[110:111], v[8:9], v[26:27] op_sel:[0,1,0] op_sel_hi:[1,1,1]
	v_add_f32_dpp v35, v35, v35 quad_perm:[1,0,3,2] row_mask:0xf bank_mask:0xf bound_ctrl:1
	v_pk_fma_f32 v[0:1], v[0:1], v[104:105], v[20:21]
	v_pk_fma_f32 v[2:3], v[2:3], v[106:107], v[22:23]
	v_pk_fma_f32 v[4:5], v[4:5], v[104:105], v[24:25]
	v_add_f32_dpp v35, v35, v35 quad_perm:[2,3,0,1] row_mask:0xf bank_mask:0xf bound_ctrl:1
	v_pk_fma_f32 v[6:7], v[6:7], v[106:107], v[26:27]
	v_pk_mul_f32 v[28:29], v[0:1], v[116:117]
	v_pk_fma_f32 v[38:39], v[8:9], v[122:123], v[38:39] op_sel_hi:[1,0,1]
	v_add_f32_dpp v35, v35, v35 row_half_mirror row_mask:0xf bank_mask:0xf bound_ctrl:1
	v_pk_mul_f32 v[30:31], v[4:5], v[116:117]
	v_pk_fma_f32 v[28:29], v[2:3], v[118:119], v[28:29]
	v_pk_fma_f32 v[30:31], v[6:7], v[118:119], v[30:31]
	v_mov_b32_dpp v34, v35 row_ror:8 row_mask:0xf bank_mask:0xf
	v_add_f32_e32 v16, v28, v29
	v_add_f32_e32 v17, v30, v31
	v_cndmask_b32_e64 v32, v34, v35, s[6:7]
	v_cndmask_b32_e64 v33, v35, v34, s[6:7]
	v_cndmask_b32_e64 v18, v16, v17, s[6:7]
	v_cndmask_b32_e64 v19, v17, v16, s[6:7]
	v_pk_add_f32 v[8:9], v[32:33], v[38:39] neg_lo:[1,1] neg_hi:[1,1]
	s_nop 0
	v_add_f32_dpp v36, v18, v19 row_ror:8 row_mask:0xf bank_mask:0xf bound_ctrl:1
	ds_write_b32 v13, v36 offset:512
	s_waitcnt lgkmcnt(9)
	ds_read_b128 v[100:103], v10 offset:1280
	ds_read_b64 v[120:121], v11 offset:1280
	ds_read_b128 v[112:115], v10 offset:13568
	ds_read_b128 v[108:111], v10 offset:9472
	ds_read_b128 v[104:107], v10 offset:5376
	ds_read_b64 v[122:123], v12 offset:40
	ds_read_b128 v[116:119], v10 offset:17664
	v_pk_mul_f32 v[16:17], v[0:1], v[52:53]
	v_pk_mul_f32 v[18:19], v[4:5], v[52:53]
	v_pk_mul_f32 v[14:15], v[72:73], s[4:5] op_sel_hi:[1,0]
	v_pk_fma_f32 v[16:17], v[2:3], v[54:55], v[16:17]
	v_pk_fma_f32 v[18:19], v[6:7], v[54:55], v[18:19]
	v_pk_mul_f32 v[20:21], v[64:65], v[14:15] op_sel_hi:[1,0]
	v_pk_mul_f32 v[22:23], v[66:67], v[14:15] op_sel_hi:[1,0]
	v_add_f32_e32 v32, v16, v17
	v_add_f32_e32 v33, v18, v19
	v_pk_mul_f32 v[24:25], v[64:65], v[14:15] op_sel:[0,1] op_sel_hi:[1,1]
	v_pk_mul_f32 v[26:27], v[66:67], v[14:15] op_sel:[0,1] op_sel_hi:[1,1]
	v_cndmask_b32_e64 v34, v32, v33, s[6:7]
	v_cndmask_b32_e64 v35, v33, v32, s[6:7]
	v_pk_mul_f32 v[38:39], v[14:15], v[74:75] op_sel:[0,1] op_sel_hi:[1,1]
	v_pk_fma_f32 v[20:21], v[60:61], v[8:9], v[20:21] op_sel_hi:[1,0,1]
	v_add_f32_dpp v35, v34, v35 row_ror:8 row_mask:0xf bank_mask:0xf bound_ctrl:1
	v_pk_fma_f32 v[22:23], v[62:63], v[8:9], v[22:23] op_sel_hi:[1,0,1]
	v_pk_fma_f32 v[24:25], v[60:61], v[8:9], v[24:25] op_sel:[0,1,0] op_sel_hi:[1,1,1]
	v_pk_fma_f32 v[26:27], v[62:63], v[8:9], v[26:27] op_sel:[0,1,0] op_sel_hi:[1,1,1]
	v_add_f32_dpp v35, v35, v35 quad_perm:[1,0,3,2] row_mask:0xf bank_mask:0xf bound_ctrl:1
	v_pk_fma_f32 v[0:1], v[0:1], v[56:57], v[20:21]
	v_pk_fma_f32 v[2:3], v[2:3], v[58:59], v[22:23]
	v_pk_fma_f32 v[4:5], v[4:5], v[56:57], v[24:25]
	v_add_f32_dpp v35, v35, v35 quad_perm:[2,3,0,1] row_mask:0xf bank_mask:0xf bound_ctrl:1
	v_pk_fma_f32 v[6:7], v[6:7], v[58:59], v[26:27]
	v_pk_mul_f32 v[28:29], v[0:1], v[68:69]
	v_pk_fma_f32 v[38:39], v[8:9], v[74:75], v[38:39] op_sel_hi:[1,0,1]
	v_add_f32_dpp v35, v35, v35 row_half_mirror row_mask:0xf bank_mask:0xf bound_ctrl:1
	v_pk_mul_f32 v[30:31], v[4:5], v[68:69]
	v_pk_fma_f32 v[28:29], v[2:3], v[70:71], v[28:29]
	v_pk_fma_f32 v[30:31], v[6:7], v[70:71], v[30:31]
	v_mov_b32_dpp v34, v35 row_ror:8 row_mask:0xf bank_mask:0xf
	v_add_f32_e32 v16, v28, v29
	v_add_f32_e32 v17, v30, v31
	v_cndmask_b32_e64 v32, v34, v35, s[6:7]
	v_cndmask_b32_e64 v33, v35, v34, s[6:7]
	v_cndmask_b32_e64 v18, v16, v17, s[6:7]
	v_cndmask_b32_e64 v19, v17, v16, s[6:7]
	v_pk_add_f32 v[8:9], v[32:33], v[38:39] neg_lo:[1,1] neg_hi:[1,1]
	s_nop 0
	v_add_f32_dpp v36, v18, v19 row_ror:8 row_mask:0xf bank_mask:0xf bound_ctrl:1
	ds_write_b32 v13, v36 offset:768
	s_waitcnt lgkmcnt(9)
	ds_read_b128 v[52:55], v10 offset:1536
	ds_read_b64 v[72:73], v11 offset:1536
	ds_read_b128 v[64:67], v10 offset:13824
	ds_read_b128 v[60:63], v10 offset:9728
	ds_read_b128 v[56:59], v10 offset:5632
	ds_read_b64 v[74:75], v12 offset:48
	ds_read_b128 v[68:71], v10 offset:17920
	v_pk_mul_f32 v[16:17], v[0:1], v[76:77]
	v_pk_mul_f32 v[18:19], v[4:5], v[76:77]
	v_pk_mul_f32 v[14:15], v[96:97], s[4:5] op_sel_hi:[1,0]
	v_pk_fma_f32 v[16:17], v[2:3], v[78:79], v[16:17]
	v_pk_fma_f32 v[18:19], v[6:7], v[78:79], v[18:19]
	v_pk_mul_f32 v[20:21], v[88:89], v[14:15] op_sel_hi:[1,0]
	v_pk_mul_f32 v[22:23], v[90:91], v[14:15] op_sel_hi:[1,0]
	v_add_f32_e32 v32, v16, v17
	v_add_f32_e32 v33, v18, v19
	v_pk_mul_f32 v[24:25], v[88:89], v[14:15] op_sel:[0,1] op_sel_hi:[1,1]
	v_pk_mul_f32 v[26:27], v[90:91], v[14:15] op_sel:[0,1] op_sel_hi:[1,1]
	v_cndmask_b32_e64 v34, v32, v33, s[6:7]
	v_cndmask_b32_e64 v35, v33, v32, s[6:7]
	v_pk_mul_f32 v[38:39], v[14:15], v[98:99] op_sel:[0,1] op_sel_hi:[1,1]
	v_pk_fma_f32 v[20:21], v[84:85], v[8:9], v[20:21] op_sel_hi:[1,0,1]
	v_add_f32_dpp v35, v34, v35 row_ror:8 row_mask:0xf bank_mask:0xf bound_ctrl:1
	v_pk_fma_f32 v[22:23], v[86:87], v[8:9], v[22:23] op_sel_hi:[1,0,1]
	v_pk_fma_f32 v[24:25], v[84:85], v[8:9], v[24:25] op_sel:[0,1,0] op_sel_hi:[1,1,1]
	v_pk_fma_f32 v[26:27], v[86:87], v[8:9], v[26:27] op_sel:[0,1,0] op_sel_hi:[1,1,1]
	v_add_f32_dpp v35, v35, v35 quad_perm:[1,0,3,2] row_mask:0xf bank_mask:0xf bound_ctrl:1
	v_pk_fma_f32 v[0:1], v[0:1], v[80:81], v[20:21]
	v_pk_fma_f32 v[2:3], v[2:3], v[82:83], v[22:23]
	v_pk_fma_f32 v[4:5], v[4:5], v[80:81], v[24:25]
	v_add_f32_dpp v35, v35, v35 quad_perm:[2,3,0,1] row_mask:0xf bank_mask:0xf bound_ctrl:1
	v_pk_fma_f32 v[6:7], v[6:7], v[82:83], v[26:27]
	v_pk_mul_f32 v[28:29], v[0:1], v[92:93]
	v_pk_fma_f32 v[38:39], v[8:9], v[98:99], v[38:39] op_sel_hi:[1,0,1]
	v_add_f32_dpp v35, v35, v35 row_half_mirror row_mask:0xf bank_mask:0xf bound_ctrl:1
	v_pk_mul_f32 v[30:31], v[4:5], v[92:93]
	v_pk_fma_f32 v[28:29], v[2:3], v[94:95], v[28:29]
	v_pk_fma_f32 v[30:31], v[6:7], v[94:95], v[30:31]
	v_mov_b32_dpp v34, v35 row_ror:8 row_mask:0xf bank_mask:0xf
	v_add_f32_e32 v16, v28, v29
	v_add_f32_e32 v17, v30, v31
	v_cndmask_b32_e64 v32, v34, v35, s[6:7]
	v_cndmask_b32_e64 v33, v35, v34, s[6:7]
	v_cndmask_b32_e64 v18, v16, v17, s[6:7]
	v_cndmask_b32_e64 v19, v17, v16, s[6:7]
	v_pk_add_f32 v[8:9], v[32:33], v[38:39] neg_lo:[1,1] neg_hi:[1,1]
	s_nop 0
	v_add_f32_dpp v36, v18, v19 row_ror:8 row_mask:0xf bank_mask:0xf bound_ctrl:1
	ds_write_b32 v13, v36 offset:1024
	s_waitcnt lgkmcnt(9)
	ds_read_b128 v[76:79], v10 offset:1792
	ds_read_b64 v[96:97], v11 offset:1792
	ds_read_b128 v[88:91], v10 offset:14080
	ds_read_b128 v[84:87], v10 offset:9984
	ds_read_b128 v[80:83], v10 offset:5888
	ds_read_b64 v[98:99], v12 offset:56
	ds_read_b128 v[92:95], v10 offset:18176
	v_pk_mul_f32 v[16:17], v[0:1], v[100:101]
	v_pk_mul_f32 v[18:19], v[4:5], v[100:101]
	v_pk_mul_f32 v[14:15], v[120:121], s[4:5] op_sel_hi:[1,0]
	v_pk_fma_f32 v[16:17], v[2:3], v[102:103], v[16:17]
	v_pk_fma_f32 v[18:19], v[6:7], v[102:103], v[18:19]
	v_pk_mul_f32 v[20:21], v[112:113], v[14:15] op_sel_hi:[1,0]
	v_pk_mul_f32 v[22:23], v[114:115], v[14:15] op_sel_hi:[1,0]
	v_add_f32_e32 v32, v16, v17
	v_add_f32_e32 v33, v18, v19
	v_pk_mul_f32 v[24:25], v[112:113], v[14:15] op_sel:[0,1] op_sel_hi:[1,1]
	v_pk_mul_f32 v[26:27], v[114:115], v[14:15] op_sel:[0,1] op_sel_hi:[1,1]
	v_cndmask_b32_e64 v34, v32, v33, s[6:7]
	v_cndmask_b32_e64 v35, v33, v32, s[6:7]
	v_pk_mul_f32 v[38:39], v[14:15], v[122:123] op_sel:[0,1] op_sel_hi:[1,1]
	v_pk_fma_f32 v[20:21], v[108:109], v[8:9], v[20:21] op_sel_hi:[1,0,1]
	v_add_f32_dpp v35, v34, v35 row_ror:8 row_mask:0xf bank_mask:0xf bound_ctrl:1
	v_pk_fma_f32 v[22:23], v[110:111], v[8:9], v[22:23] op_sel_hi:[1,0,1]
	v_pk_fma_f32 v[24:25], v[108:109], v[8:9], v[24:25] op_sel:[0,1,0] op_sel_hi:[1,1,1]
	v_pk_fma_f32 v[26:27], v[110:111], v[8:9], v[26:27] op_sel:[0,1,0] op_sel_hi:[1,1,1]
	v_add_f32_dpp v35, v35, v35 quad_perm:[1,0,3,2] row_mask:0xf bank_mask:0xf bound_ctrl:1
	v_pk_fma_f32 v[0:1], v[0:1], v[104:105], v[20:21]
	v_pk_fma_f32 v[2:3], v[2:3], v[106:107], v[22:23]
	v_pk_fma_f32 v[4:5], v[4:5], v[104:105], v[24:25]
	v_add_f32_dpp v35, v35, v35 quad_perm:[2,3,0,1] row_mask:0xf bank_mask:0xf bound_ctrl:1
	v_pk_fma_f32 v[6:7], v[6:7], v[106:107], v[26:27]
	v_pk_mul_f32 v[28:29], v[0:1], v[116:117]
	v_pk_fma_f32 v[38:39], v[8:9], v[122:123], v[38:39] op_sel_hi:[1,0,1]
	v_add_f32_dpp v35, v35, v35 row_half_mirror row_mask:0xf bank_mask:0xf bound_ctrl:1
	v_pk_mul_f32 v[30:31], v[4:5], v[116:117]
	v_pk_fma_f32 v[28:29], v[2:3], v[118:119], v[28:29]
	v_pk_fma_f32 v[30:31], v[6:7], v[118:119], v[30:31]
	v_mov_b32_dpp v34, v35 row_ror:8 row_mask:0xf bank_mask:0xf
	v_add_f32_e32 v16, v28, v29
	v_add_f32_e32 v17, v30, v31
	v_cndmask_b32_e64 v32, v34, v35, s[6:7]
	v_cndmask_b32_e64 v33, v35, v34, s[6:7]
	v_cndmask_b32_e64 v18, v16, v17, s[6:7]
	v_cndmask_b32_e64 v19, v17, v16, s[6:7]
	v_pk_add_f32 v[8:9], v[32:33], v[38:39] neg_lo:[1,1] neg_hi:[1,1]
	s_nop 0
	v_add_f32_dpp v36, v18, v19 row_ror:8 row_mask:0xf bank_mask:0xf bound_ctrl:1
	ds_write_b32 v13, v36 offset:1280
	s_waitcnt lgkmcnt(9)
	ds_read_b128 v[100:103], v10 offset:2048
	ds_read_b64 v[120:121], v11 offset:2048
	ds_read_b128 v[112:115], v10 offset:14336
	ds_read_b128 v[108:111], v10 offset:10240
	ds_read_b128 v[104:107], v10 offset:6144
	ds_read_b64 v[122:123], v12 offset:64
	ds_read_b128 v[116:119], v10 offset:18432
	v_pk_mul_f32 v[16:17], v[0:1], v[52:53]
	v_pk_mul_f32 v[18:19], v[4:5], v[52:53]
	v_pk_mul_f32 v[14:15], v[72:73], s[4:5] op_sel_hi:[1,0]
	v_pk_fma_f32 v[16:17], v[2:3], v[54:55], v[16:17]
	v_pk_fma_f32 v[18:19], v[6:7], v[54:55], v[18:19]
	v_pk_mul_f32 v[20:21], v[64:65], v[14:15] op_sel_hi:[1,0]
	v_pk_mul_f32 v[22:23], v[66:67], v[14:15] op_sel_hi:[1,0]
	v_add_f32_e32 v32, v16, v17
	v_add_f32_e32 v33, v18, v19
	v_pk_mul_f32 v[24:25], v[64:65], v[14:15] op_sel:[0,1] op_sel_hi:[1,1]
	v_pk_mul_f32 v[26:27], v[66:67], v[14:15] op_sel:[0,1] op_sel_hi:[1,1]
	v_cndmask_b32_e64 v34, v32, v33, s[6:7]
	v_cndmask_b32_e64 v35, v33, v32, s[6:7]
	v_pk_mul_f32 v[38:39], v[14:15], v[74:75] op_sel:[0,1] op_sel_hi:[1,1]
	v_pk_fma_f32 v[20:21], v[60:61], v[8:9], v[20:21] op_sel_hi:[1,0,1]
	v_add_f32_dpp v35, v34, v35 row_ror:8 row_mask:0xf bank_mask:0xf bound_ctrl:1
	v_pk_fma_f32 v[22:23], v[62:63], v[8:9], v[22:23] op_sel_hi:[1,0,1]
	v_pk_fma_f32 v[24:25], v[60:61], v[8:9], v[24:25] op_sel:[0,1,0] op_sel_hi:[1,1,1]
	v_pk_fma_f32 v[26:27], v[62:63], v[8:9], v[26:27] op_sel:[0,1,0] op_sel_hi:[1,1,1]
	v_add_f32_dpp v35, v35, v35 quad_perm:[1,0,3,2] row_mask:0xf bank_mask:0xf bound_ctrl:1
	v_pk_fma_f32 v[0:1], v[0:1], v[56:57], v[20:21]
	v_pk_fma_f32 v[2:3], v[2:3], v[58:59], v[22:23]
	v_pk_fma_f32 v[4:5], v[4:5], v[56:57], v[24:25]
	v_add_f32_dpp v35, v35, v35 quad_perm:[2,3,0,1] row_mask:0xf bank_mask:0xf bound_ctrl:1
	v_pk_fma_f32 v[6:7], v[6:7], v[58:59], v[26:27]
	v_pk_mul_f32 v[28:29], v[0:1], v[68:69]
	v_pk_fma_f32 v[38:39], v[8:9], v[74:75], v[38:39] op_sel_hi:[1,0,1]
	v_add_f32_dpp v35, v35, v35 row_half_mirror row_mask:0xf bank_mask:0xf bound_ctrl:1
	v_pk_mul_f32 v[30:31], v[4:5], v[68:69]
	v_pk_fma_f32 v[28:29], v[2:3], v[70:71], v[28:29]
	v_pk_fma_f32 v[30:31], v[6:7], v[70:71], v[30:31]
	v_mov_b32_dpp v34, v35 row_ror:8 row_mask:0xf bank_mask:0xf
	v_add_f32_e32 v16, v28, v29
	v_add_f32_e32 v17, v30, v31
	v_cndmask_b32_e64 v32, v34, v35, s[6:7]
	v_cndmask_b32_e64 v33, v35, v34, s[6:7]
	v_cndmask_b32_e64 v18, v16, v17, s[6:7]
	v_cndmask_b32_e64 v19, v17, v16, s[6:7]
	v_pk_add_f32 v[8:9], v[32:33], v[38:39] neg_lo:[1,1] neg_hi:[1,1]
	s_nop 0
	v_add_f32_dpp v36, v18, v19 row_ror:8 row_mask:0xf bank_mask:0xf bound_ctrl:1
	ds_write_b32 v13, v36 offset:1536
	s_waitcnt lgkmcnt(9)
	ds_read_b128 v[52:55], v10 offset:2304
	ds_read_b64 v[72:73], v11 offset:2304
	ds_read_b128 v[64:67], v10 offset:14592
	ds_read_b128 v[60:63], v10 offset:10496
	ds_read_b128 v[56:59], v10 offset:6400
	ds_read_b64 v[74:75], v12 offset:72
	ds_read_b128 v[68:71], v10 offset:18688
	v_pk_mul_f32 v[16:17], v[0:1], v[76:77]
	v_pk_mul_f32 v[18:19], v[4:5], v[76:77]
	v_pk_mul_f32 v[14:15], v[96:97], s[4:5] op_sel_hi:[1,0]
	v_pk_fma_f32 v[16:17], v[2:3], v[78:79], v[16:17]
	v_pk_fma_f32 v[18:19], v[6:7], v[78:79], v[18:19]
	v_pk_mul_f32 v[20:21], v[88:89], v[14:15] op_sel_hi:[1,0]
	v_pk_mul_f32 v[22:23], v[90:91], v[14:15] op_sel_hi:[1,0]
	v_add_f32_e32 v32, v16, v17
	v_add_f32_e32 v33, v18, v19
	v_pk_mul_f32 v[24:25], v[88:89], v[14:15] op_sel:[0,1] op_sel_hi:[1,1]
	v_pk_mul_f32 v[26:27], v[90:91], v[14:15] op_sel:[0,1] op_sel_hi:[1,1]
	v_cndmask_b32_e64 v34, v32, v33, s[6:7]
	v_cndmask_b32_e64 v35, v33, v32, s[6:7]
	v_pk_mul_f32 v[38:39], v[14:15], v[98:99] op_sel:[0,1] op_sel_hi:[1,1]
	v_pk_fma_f32 v[20:21], v[84:85], v[8:9], v[20:21] op_sel_hi:[1,0,1]
	v_add_f32_dpp v35, v34, v35 row_ror:8 row_mask:0xf bank_mask:0xf bound_ctrl:1
	v_pk_fma_f32 v[22:23], v[86:87], v[8:9], v[22:23] op_sel_hi:[1,0,1]
	v_pk_fma_f32 v[24:25], v[84:85], v[8:9], v[24:25] op_sel:[0,1,0] op_sel_hi:[1,1,1]
	v_pk_fma_f32 v[26:27], v[86:87], v[8:9], v[26:27] op_sel:[0,1,0] op_sel_hi:[1,1,1]
	v_add_f32_dpp v35, v35, v35 quad_perm:[1,0,3,2] row_mask:0xf bank_mask:0xf bound_ctrl:1
	v_pk_fma_f32 v[0:1], v[0:1], v[80:81], v[20:21]
	v_pk_fma_f32 v[2:3], v[2:3], v[82:83], v[22:23]
	v_pk_fma_f32 v[4:5], v[4:5], v[80:81], v[24:25]
	v_add_f32_dpp v35, v35, v35 quad_perm:[2,3,0,1] row_mask:0xf bank_mask:0xf bound_ctrl:1
	v_pk_fma_f32 v[6:7], v[6:7], v[82:83], v[26:27]
	v_pk_mul_f32 v[28:29], v[0:1], v[92:93]
	v_pk_fma_f32 v[38:39], v[8:9], v[98:99], v[38:39] op_sel_hi:[1,0,1]
	v_add_f32_dpp v35, v35, v35 row_half_mirror row_mask:0xf bank_mask:0xf bound_ctrl:1
	v_pk_mul_f32 v[30:31], v[4:5], v[92:93]
	v_pk_fma_f32 v[28:29], v[2:3], v[94:95], v[28:29]
	v_pk_fma_f32 v[30:31], v[6:7], v[94:95], v[30:31]
	v_mov_b32_dpp v34, v35 row_ror:8 row_mask:0xf bank_mask:0xf
	v_add_f32_e32 v16, v28, v29
	v_add_f32_e32 v17, v30, v31
	v_cndmask_b32_e64 v32, v34, v35, s[6:7]
	v_cndmask_b32_e64 v33, v35, v34, s[6:7]
	v_cndmask_b32_e64 v18, v16, v17, s[6:7]
	v_cndmask_b32_e64 v19, v17, v16, s[6:7]
	v_pk_add_f32 v[8:9], v[32:33], v[38:39] neg_lo:[1,1] neg_hi:[1,1]
	s_nop 0
	v_add_f32_dpp v36, v18, v19 row_ror:8 row_mask:0xf bank_mask:0xf bound_ctrl:1
	ds_write_b32 v13, v36 offset:1792
	s_waitcnt lgkmcnt(9)
	ds_read_b128 v[76:79], v10 offset:2560
	ds_read_b64 v[96:97], v11 offset:2560
	ds_read_b128 v[88:91], v10 offset:14848
	ds_read_b128 v[84:87], v10 offset:10752
	ds_read_b128 v[80:83], v10 offset:6656
	ds_read_b64 v[98:99], v12 offset:80
	ds_read_b128 v[92:95], v10 offset:18944
	v_pk_mul_f32 v[16:17], v[0:1], v[100:101]
	v_pk_mul_f32 v[18:19], v[4:5], v[100:101]
	v_pk_mul_f32 v[14:15], v[120:121], s[4:5] op_sel_hi:[1,0]
	v_pk_fma_f32 v[16:17], v[2:3], v[102:103], v[16:17]
	v_pk_fma_f32 v[18:19], v[6:7], v[102:103], v[18:19]
	v_pk_mul_f32 v[20:21], v[112:113], v[14:15] op_sel_hi:[1,0]
	v_pk_mul_f32 v[22:23], v[114:115], v[14:15] op_sel_hi:[1,0]
	v_add_f32_e32 v32, v16, v17
	v_add_f32_e32 v33, v18, v19
	v_pk_mul_f32 v[24:25], v[112:113], v[14:15] op_sel:[0,1] op_sel_hi:[1,1]
	v_pk_mul_f32 v[26:27], v[114:115], v[14:15] op_sel:[0,1] op_sel_hi:[1,1]
	v_cndmask_b32_e64 v34, v32, v33, s[6:7]
	v_cndmask_b32_e64 v35, v33, v32, s[6:7]
	v_pk_mul_f32 v[38:39], v[14:15], v[122:123] op_sel:[0,1] op_sel_hi:[1,1]
	v_pk_fma_f32 v[20:21], v[108:109], v[8:9], v[20:21] op_sel_hi:[1,0,1]
	v_add_f32_dpp v35, v34, v35 row_ror:8 row_mask:0xf bank_mask:0xf bound_ctrl:1
	v_pk_fma_f32 v[22:23], v[110:111], v[8:9], v[22:23] op_sel_hi:[1,0,1]
	v_pk_fma_f32 v[24:25], v[108:109], v[8:9], v[24:25] op_sel:[0,1,0] op_sel_hi:[1,1,1]
	v_pk_fma_f32 v[26:27], v[110:111], v[8:9], v[26:27] op_sel:[0,1,0] op_sel_hi:[1,1,1]
	v_add_f32_dpp v35, v35, v35 quad_perm:[1,0,3,2] row_mask:0xf bank_mask:0xf bound_ctrl:1
	v_pk_fma_f32 v[0:1], v[0:1], v[104:105], v[20:21]
	v_pk_fma_f32 v[2:3], v[2:3], v[106:107], v[22:23]
	v_pk_fma_f32 v[4:5], v[4:5], v[104:105], v[24:25]
	v_add_f32_dpp v35, v35, v35 quad_perm:[2,3,0,1] row_mask:0xf bank_mask:0xf bound_ctrl:1
	v_pk_fma_f32 v[6:7], v[6:7], v[106:107], v[26:27]
	v_pk_mul_f32 v[28:29], v[0:1], v[116:117]
	v_pk_fma_f32 v[38:39], v[8:9], v[122:123], v[38:39] op_sel_hi:[1,0,1]
	v_add_f32_dpp v35, v35, v35 row_half_mirror row_mask:0xf bank_mask:0xf bound_ctrl:1
	v_pk_mul_f32 v[30:31], v[4:5], v[116:117]
	v_pk_fma_f32 v[28:29], v[2:3], v[118:119], v[28:29]
	v_pk_fma_f32 v[30:31], v[6:7], v[118:119], v[30:31]
	v_mov_b32_dpp v34, v35 row_ror:8 row_mask:0xf bank_mask:0xf
	v_add_f32_e32 v16, v28, v29
	v_add_f32_e32 v17, v30, v31
	v_cndmask_b32_e64 v32, v34, v35, s[6:7]
	v_cndmask_b32_e64 v33, v35, v34, s[6:7]
	v_cndmask_b32_e64 v18, v16, v17, s[6:7]
	v_cndmask_b32_e64 v19, v17, v16, s[6:7]
	v_pk_add_f32 v[8:9], v[32:33], v[38:39] neg_lo:[1,1] neg_hi:[1,1]
	s_nop 0
	v_add_f32_dpp v36, v18, v19 row_ror:8 row_mask:0xf bank_mask:0xf bound_ctrl:1
	ds_write_b32 v13, v36 offset:2048
	s_waitcnt lgkmcnt(9)
	ds_read_b128 v[100:103], v10 offset:2816
	ds_read_b64 v[120:121], v11 offset:2816
	ds_read_b128 v[112:115], v10 offset:15104
	ds_read_b128 v[108:111], v10 offset:11008
	ds_read_b128 v[104:107], v10 offset:6912
	ds_read_b64 v[122:123], v12 offset:88
	ds_read_b128 v[116:119], v10 offset:19200
	v_pk_mul_f32 v[16:17], v[0:1], v[52:53]
	v_pk_mul_f32 v[18:19], v[4:5], v[52:53]
	v_pk_mul_f32 v[14:15], v[72:73], s[4:5] op_sel_hi:[1,0]
	v_pk_fma_f32 v[16:17], v[2:3], v[54:55], v[16:17]
	v_pk_fma_f32 v[18:19], v[6:7], v[54:55], v[18:19]
	v_pk_mul_f32 v[20:21], v[64:65], v[14:15] op_sel_hi:[1,0]
	v_pk_mul_f32 v[22:23], v[66:67], v[14:15] op_sel_hi:[1,0]
	v_add_f32_e32 v32, v16, v17
	v_add_f32_e32 v33, v18, v19
	v_pk_mul_f32 v[24:25], v[64:65], v[14:15] op_sel:[0,1] op_sel_hi:[1,1]
	v_pk_mul_f32 v[26:27], v[66:67], v[14:15] op_sel:[0,1] op_sel_hi:[1,1]
	v_cndmask_b32_e64 v34, v32, v33, s[6:7]
	v_cndmask_b32_e64 v35, v33, v32, s[6:7]
	v_pk_mul_f32 v[38:39], v[14:15], v[74:75] op_sel:[0,1] op_sel_hi:[1,1]
	v_pk_fma_f32 v[20:21], v[60:61], v[8:9], v[20:21] op_sel_hi:[1,0,1]
	v_add_f32_dpp v35, v34, v35 row_ror:8 row_mask:0xf bank_mask:0xf bound_ctrl:1
	v_pk_fma_f32 v[22:23], v[62:63], v[8:9], v[22:23] op_sel_hi:[1,0,1]
	v_pk_fma_f32 v[24:25], v[60:61], v[8:9], v[24:25] op_sel:[0,1,0] op_sel_hi:[1,1,1]
	v_pk_fma_f32 v[26:27], v[62:63], v[8:9], v[26:27] op_sel:[0,1,0] op_sel_hi:[1,1,1]
	v_add_f32_dpp v35, v35, v35 quad_perm:[1,0,3,2] row_mask:0xf bank_mask:0xf bound_ctrl:1
	v_pk_fma_f32 v[0:1], v[0:1], v[56:57], v[20:21]
	v_pk_fma_f32 v[2:3], v[2:3], v[58:59], v[22:23]
	v_pk_fma_f32 v[4:5], v[4:5], v[56:57], v[24:25]
	v_add_f32_dpp v35, v35, v35 quad_perm:[2,3,0,1] row_mask:0xf bank_mask:0xf bound_ctrl:1
	v_pk_fma_f32 v[6:7], v[6:7], v[58:59], v[26:27]
	v_pk_mul_f32 v[28:29], v[0:1], v[68:69]
	v_pk_fma_f32 v[38:39], v[8:9], v[74:75], v[38:39] op_sel_hi:[1,0,1]
	v_add_f32_dpp v35, v35, v35 row_half_mirror row_mask:0xf bank_mask:0xf bound_ctrl:1
	v_pk_mul_f32 v[30:31], v[4:5], v[68:69]
	v_pk_fma_f32 v[28:29], v[2:3], v[70:71], v[28:29]
	v_pk_fma_f32 v[30:31], v[6:7], v[70:71], v[30:31]
	v_mov_b32_dpp v34, v35 row_ror:8 row_mask:0xf bank_mask:0xf
	v_add_f32_e32 v16, v28, v29
	v_add_f32_e32 v17, v30, v31
	v_cndmask_b32_e64 v32, v34, v35, s[6:7]
	v_cndmask_b32_e64 v33, v35, v34, s[6:7]
	v_cndmask_b32_e64 v18, v16, v17, s[6:7]
	v_cndmask_b32_e64 v19, v17, v16, s[6:7]
	v_pk_add_f32 v[8:9], v[32:33], v[38:39] neg_lo:[1,1] neg_hi:[1,1]
	s_nop 0
	v_add_f32_dpp v36, v18, v19 row_ror:8 row_mask:0xf bank_mask:0xf bound_ctrl:1
	ds_write_b32 v13, v36 offset:2304
	s_waitcnt lgkmcnt(9)
	ds_read_b128 v[52:55], v10 offset:3072
	ds_read_b64 v[72:73], v11 offset:3072
	ds_read_b128 v[64:67], v10 offset:15360
	ds_read_b128 v[60:63], v10 offset:11264
	ds_read_b128 v[56:59], v10 offset:7168
	ds_read_b64 v[74:75], v12 offset:96
	ds_read_b128 v[68:71], v10 offset:19456
	v_pk_mul_f32 v[16:17], v[0:1], v[76:77]
	v_pk_mul_f32 v[18:19], v[4:5], v[76:77]
	v_pk_mul_f32 v[14:15], v[96:97], s[4:5] op_sel_hi:[1,0]
	v_pk_fma_f32 v[16:17], v[2:3], v[78:79], v[16:17]
	v_pk_fma_f32 v[18:19], v[6:7], v[78:79], v[18:19]
	v_pk_mul_f32 v[20:21], v[88:89], v[14:15] op_sel_hi:[1,0]
	v_pk_mul_f32 v[22:23], v[90:91], v[14:15] op_sel_hi:[1,0]
	v_add_f32_e32 v32, v16, v17
	v_add_f32_e32 v33, v18, v19
	v_pk_mul_f32 v[24:25], v[88:89], v[14:15] op_sel:[0,1] op_sel_hi:[1,1]
	v_pk_mul_f32 v[26:27], v[90:91], v[14:15] op_sel:[0,1] op_sel_hi:[1,1]
	v_cndmask_b32_e64 v34, v32, v33, s[6:7]
	v_cndmask_b32_e64 v35, v33, v32, s[6:7]
	v_pk_mul_f32 v[38:39], v[14:15], v[98:99] op_sel:[0,1] op_sel_hi:[1,1]
	v_pk_fma_f32 v[20:21], v[84:85], v[8:9], v[20:21] op_sel_hi:[1,0,1]
	v_add_f32_dpp v35, v34, v35 row_ror:8 row_mask:0xf bank_mask:0xf bound_ctrl:1
	v_pk_fma_f32 v[22:23], v[86:87], v[8:9], v[22:23] op_sel_hi:[1,0,1]
	v_pk_fma_f32 v[24:25], v[84:85], v[8:9], v[24:25] op_sel:[0,1,0] op_sel_hi:[1,1,1]
	v_pk_fma_f32 v[26:27], v[86:87], v[8:9], v[26:27] op_sel:[0,1,0] op_sel_hi:[1,1,1]
	v_add_f32_dpp v35, v35, v35 quad_perm:[1,0,3,2] row_mask:0xf bank_mask:0xf bound_ctrl:1
	v_pk_fma_f32 v[0:1], v[0:1], v[80:81], v[20:21]
	v_pk_fma_f32 v[2:3], v[2:3], v[82:83], v[22:23]
	v_pk_fma_f32 v[4:5], v[4:5], v[80:81], v[24:25]
	v_add_f32_dpp v35, v35, v35 quad_perm:[2,3,0,1] row_mask:0xf bank_mask:0xf bound_ctrl:1
	v_pk_fma_f32 v[6:7], v[6:7], v[82:83], v[26:27]
	v_pk_mul_f32 v[28:29], v[0:1], v[92:93]
	v_pk_fma_f32 v[38:39], v[8:9], v[98:99], v[38:39] op_sel_hi:[1,0,1]
	v_add_f32_dpp v35, v35, v35 row_half_mirror row_mask:0xf bank_mask:0xf bound_ctrl:1
	v_pk_mul_f32 v[30:31], v[4:5], v[92:93]
	v_pk_fma_f32 v[28:29], v[2:3], v[94:95], v[28:29]
	v_pk_fma_f32 v[30:31], v[6:7], v[94:95], v[30:31]
	v_mov_b32_dpp v34, v35 row_ror:8 row_mask:0xf bank_mask:0xf
	v_add_f32_e32 v16, v28, v29
	v_add_f32_e32 v17, v30, v31
	v_cndmask_b32_e64 v32, v34, v35, s[6:7]
	v_cndmask_b32_e64 v33, v35, v34, s[6:7]
	v_cndmask_b32_e64 v18, v16, v17, s[6:7]
	v_cndmask_b32_e64 v19, v17, v16, s[6:7]
	v_pk_add_f32 v[8:9], v[32:33], v[38:39] neg_lo:[1,1] neg_hi:[1,1]
	s_nop 0
	v_add_f32_dpp v36, v18, v19 row_ror:8 row_mask:0xf bank_mask:0xf bound_ctrl:1
	ds_write_b32 v13, v36 offset:2560
	s_waitcnt lgkmcnt(9)
	ds_read_b128 v[76:79], v10 offset:3328
	ds_read_b64 v[96:97], v11 offset:3328
	ds_read_b128 v[88:91], v10 offset:15616
	ds_read_b128 v[84:87], v10 offset:11520
	ds_read_b128 v[80:83], v10 offset:7424
	ds_read_b64 v[98:99], v12 offset:104
	ds_read_b128 v[92:95], v10 offset:19712
	v_pk_mul_f32 v[16:17], v[0:1], v[100:101]
	v_pk_mul_f32 v[18:19], v[4:5], v[100:101]
	v_pk_mul_f32 v[14:15], v[120:121], s[4:5] op_sel_hi:[1,0]
	v_pk_fma_f32 v[16:17], v[2:3], v[102:103], v[16:17]
	v_pk_fma_f32 v[18:19], v[6:7], v[102:103], v[18:19]
	v_pk_mul_f32 v[20:21], v[112:113], v[14:15] op_sel_hi:[1,0]
	v_pk_mul_f32 v[22:23], v[114:115], v[14:15] op_sel_hi:[1,0]
	v_add_f32_e32 v32, v16, v17
	v_add_f32_e32 v33, v18, v19
	v_pk_mul_f32 v[24:25], v[112:113], v[14:15] op_sel:[0,1] op_sel_hi:[1,1]
	v_pk_mul_f32 v[26:27], v[114:115], v[14:15] op_sel:[0,1] op_sel_hi:[1,1]
	v_cndmask_b32_e64 v34, v32, v33, s[6:7]
	v_cndmask_b32_e64 v35, v33, v32, s[6:7]
	v_pk_mul_f32 v[38:39], v[14:15], v[122:123] op_sel:[0,1] op_sel_hi:[1,1]
	v_pk_fma_f32 v[20:21], v[108:109], v[8:9], v[20:21] op_sel_hi:[1,0,1]
	v_add_f32_dpp v35, v34, v35 row_ror:8 row_mask:0xf bank_mask:0xf bound_ctrl:1
	v_pk_fma_f32 v[22:23], v[110:111], v[8:9], v[22:23] op_sel_hi:[1,0,1]
	v_pk_fma_f32 v[24:25], v[108:109], v[8:9], v[24:25] op_sel:[0,1,0] op_sel_hi:[1,1,1]
	v_pk_fma_f32 v[26:27], v[110:111], v[8:9], v[26:27] op_sel:[0,1,0] op_sel_hi:[1,1,1]
	v_add_f32_dpp v35, v35, v35 quad_perm:[1,0,3,2] row_mask:0xf bank_mask:0xf bound_ctrl:1
	v_pk_fma_f32 v[0:1], v[0:1], v[104:105], v[20:21]
	v_pk_fma_f32 v[2:3], v[2:3], v[106:107], v[22:23]
	v_pk_fma_f32 v[4:5], v[4:5], v[104:105], v[24:25]
	v_add_f32_dpp v35, v35, v35 quad_perm:[2,3,0,1] row_mask:0xf bank_mask:0xf bound_ctrl:1
	v_pk_fma_f32 v[6:7], v[6:7], v[106:107], v[26:27]
	v_pk_mul_f32 v[28:29], v[0:1], v[116:117]
	v_pk_fma_f32 v[38:39], v[8:9], v[122:123], v[38:39] op_sel_hi:[1,0,1]
	v_add_f32_dpp v35, v35, v35 row_half_mirror row_mask:0xf bank_mask:0xf bound_ctrl:1
	v_pk_mul_f32 v[30:31], v[4:5], v[116:117]
	v_pk_fma_f32 v[28:29], v[2:3], v[118:119], v[28:29]
	v_pk_fma_f32 v[30:31], v[6:7], v[118:119], v[30:31]
	v_mov_b32_dpp v34, v35 row_ror:8 row_mask:0xf bank_mask:0xf
	v_add_f32_e32 v16, v28, v29
	v_add_f32_e32 v17, v30, v31
	v_cndmask_b32_e64 v32, v34, v35, s[6:7]
	v_cndmask_b32_e64 v33, v35, v34, s[6:7]
	v_cndmask_b32_e64 v18, v16, v17, s[6:7]
	v_cndmask_b32_e64 v19, v17, v16, s[6:7]
	v_pk_add_f32 v[8:9], v[32:33], v[38:39] neg_lo:[1,1] neg_hi:[1,1]
	s_nop 0
	v_add_f32_dpp v36, v18, v19 row_ror:8 row_mask:0xf bank_mask:0xf bound_ctrl:1
	ds_write_b32 v13, v36 offset:2816
	s_waitcnt lgkmcnt(9)
	ds_read_b128 v[100:103], v10 offset:3584
	ds_read_b64 v[120:121], v11 offset:3584
	ds_read_b128 v[112:115], v10 offset:15872
	ds_read_b128 v[108:111], v10 offset:11776
	ds_read_b128 v[104:107], v10 offset:7680
	ds_read_b64 v[122:123], v12 offset:112
	ds_read_b128 v[116:119], v10 offset:19968
	v_pk_mul_f32 v[16:17], v[0:1], v[52:53]
	v_pk_mul_f32 v[18:19], v[4:5], v[52:53]
	v_pk_mul_f32 v[14:15], v[72:73], s[4:5] op_sel_hi:[1,0]
	v_pk_fma_f32 v[16:17], v[2:3], v[54:55], v[16:17]
	v_pk_fma_f32 v[18:19], v[6:7], v[54:55], v[18:19]
	v_pk_mul_f32 v[20:21], v[64:65], v[14:15] op_sel_hi:[1,0]
	v_pk_mul_f32 v[22:23], v[66:67], v[14:15] op_sel_hi:[1,0]
	v_add_f32_e32 v32, v16, v17
	v_add_f32_e32 v33, v18, v19
	v_pk_mul_f32 v[24:25], v[64:65], v[14:15] op_sel:[0,1] op_sel_hi:[1,1]
	v_pk_mul_f32 v[26:27], v[66:67], v[14:15] op_sel:[0,1] op_sel_hi:[1,1]
	v_cndmask_b32_e64 v34, v32, v33, s[6:7]
	v_cndmask_b32_e64 v35, v33, v32, s[6:7]
	v_pk_mul_f32 v[38:39], v[14:15], v[74:75] op_sel:[0,1] op_sel_hi:[1,1]
	v_pk_fma_f32 v[20:21], v[60:61], v[8:9], v[20:21] op_sel_hi:[1,0,1]
	v_add_f32_dpp v35, v34, v35 row_ror:8 row_mask:0xf bank_mask:0xf bound_ctrl:1
	v_pk_fma_f32 v[22:23], v[62:63], v[8:9], v[22:23] op_sel_hi:[1,0,1]
	v_pk_fma_f32 v[24:25], v[60:61], v[8:9], v[24:25] op_sel:[0,1,0] op_sel_hi:[1,1,1]
	v_pk_fma_f32 v[26:27], v[62:63], v[8:9], v[26:27] op_sel:[0,1,0] op_sel_hi:[1,1,1]
	v_add_f32_dpp v35, v35, v35 quad_perm:[1,0,3,2] row_mask:0xf bank_mask:0xf bound_ctrl:1
	v_pk_fma_f32 v[0:1], v[0:1], v[56:57], v[20:21]
	v_pk_fma_f32 v[2:3], v[2:3], v[58:59], v[22:23]
	v_pk_fma_f32 v[4:5], v[4:5], v[56:57], v[24:25]
	v_add_f32_dpp v35, v35, v35 quad_perm:[2,3,0,1] row_mask:0xf bank_mask:0xf bound_ctrl:1
	v_pk_fma_f32 v[6:7], v[6:7], v[58:59], v[26:27]
	v_pk_mul_f32 v[28:29], v[0:1], v[68:69]
	v_pk_fma_f32 v[38:39], v[8:9], v[74:75], v[38:39] op_sel_hi:[1,0,1]
	v_add_f32_dpp v35, v35, v35 row_half_mirror row_mask:0xf bank_mask:0xf bound_ctrl:1
	v_pk_mul_f32 v[30:31], v[4:5], v[68:69]
	v_pk_fma_f32 v[28:29], v[2:3], v[70:71], v[28:29]
	v_pk_fma_f32 v[30:31], v[6:7], v[70:71], v[30:31]
	v_mov_b32_dpp v34, v35 row_ror:8 row_mask:0xf bank_mask:0xf
	v_add_f32_e32 v16, v28, v29
	v_add_f32_e32 v17, v30, v31
	v_cndmask_b32_e64 v32, v34, v35, s[6:7]
	v_cndmask_b32_e64 v33, v35, v34, s[6:7]
	v_cndmask_b32_e64 v18, v16, v17, s[6:7]
	v_cndmask_b32_e64 v19, v17, v16, s[6:7]
	v_pk_add_f32 v[8:9], v[32:33], v[38:39] neg_lo:[1,1] neg_hi:[1,1]
	s_nop 0
	v_add_f32_dpp v36, v18, v19 row_ror:8 row_mask:0xf bank_mask:0xf bound_ctrl:1
	ds_write_b32 v13, v36 offset:3072
	s_waitcnt lgkmcnt(9)
	ds_read_b128 v[52:55], v10 offset:3840
	ds_read_b64 v[72:73], v11 offset:3840
	ds_read_b128 v[64:67], v10 offset:16128
	ds_read_b128 v[60:63], v10 offset:12032
	ds_read_b128 v[56:59], v10 offset:7936
	ds_read_b64 v[74:75], v12 offset:120
	ds_read_b128 v[68:71], v10 offset:20224
	v_pk_mul_f32 v[16:17], v[0:1], v[76:77]
	v_pk_mul_f32 v[18:19], v[4:5], v[76:77]
	v_pk_mul_f32 v[14:15], v[96:97], s[4:5] op_sel_hi:[1,0]
	v_pk_fma_f32 v[16:17], v[2:3], v[78:79], v[16:17]
	v_pk_fma_f32 v[18:19], v[6:7], v[78:79], v[18:19]
	v_pk_mul_f32 v[20:21], v[88:89], v[14:15] op_sel_hi:[1,0]
	v_pk_mul_f32 v[22:23], v[90:91], v[14:15] op_sel_hi:[1,0]
	v_add_f32_e32 v32, v16, v17
	v_add_f32_e32 v33, v18, v19
	v_pk_mul_f32 v[24:25], v[88:89], v[14:15] op_sel:[0,1] op_sel_hi:[1,1]
	v_pk_mul_f32 v[26:27], v[90:91], v[14:15] op_sel:[0,1] op_sel_hi:[1,1]
	v_cndmask_b32_e64 v34, v32, v33, s[6:7]
	v_cndmask_b32_e64 v35, v33, v32, s[6:7]
	v_pk_mul_f32 v[38:39], v[14:15], v[98:99] op_sel:[0,1] op_sel_hi:[1,1]
	v_pk_fma_f32 v[20:21], v[84:85], v[8:9], v[20:21] op_sel_hi:[1,0,1]
	v_add_f32_dpp v35, v34, v35 row_ror:8 row_mask:0xf bank_mask:0xf bound_ctrl:1
	v_pk_fma_f32 v[22:23], v[86:87], v[8:9], v[22:23] op_sel_hi:[1,0,1]
	v_pk_fma_f32 v[24:25], v[84:85], v[8:9], v[24:25] op_sel:[0,1,0] op_sel_hi:[1,1,1]
	v_pk_fma_f32 v[26:27], v[86:87], v[8:9], v[26:27] op_sel:[0,1,0] op_sel_hi:[1,1,1]
	v_add_f32_dpp v35, v35, v35 quad_perm:[1,0,3,2] row_mask:0xf bank_mask:0xf bound_ctrl:1
	v_pk_fma_f32 v[0:1], v[0:1], v[80:81], v[20:21]
	v_pk_fma_f32 v[2:3], v[2:3], v[82:83], v[22:23]
	v_pk_fma_f32 v[4:5], v[4:5], v[80:81], v[24:25]
	v_add_f32_dpp v35, v35, v35 quad_perm:[2,3,0,1] row_mask:0xf bank_mask:0xf bound_ctrl:1
	v_pk_fma_f32 v[6:7], v[6:7], v[82:83], v[26:27]
	v_pk_mul_f32 v[28:29], v[0:1], v[92:93]
	v_pk_fma_f32 v[38:39], v[8:9], v[98:99], v[38:39] op_sel_hi:[1,0,1]
	v_add_f32_dpp v35, v35, v35 row_half_mirror row_mask:0xf bank_mask:0xf bound_ctrl:1
	v_pk_mul_f32 v[30:31], v[4:5], v[92:93]
	v_pk_fma_f32 v[28:29], v[2:3], v[94:95], v[28:29]
	v_pk_fma_f32 v[30:31], v[6:7], v[94:95], v[30:31]
	v_mov_b32_dpp v34, v35 row_ror:8 row_mask:0xf bank_mask:0xf
	v_add_f32_e32 v16, v28, v29
	v_add_f32_e32 v17, v30, v31
	v_cndmask_b32_e64 v32, v34, v35, s[6:7]
	v_cndmask_b32_e64 v33, v35, v34, s[6:7]
	v_cndmask_b32_e64 v18, v16, v17, s[6:7]
	v_cndmask_b32_e64 v19, v17, v16, s[6:7]
	v_pk_add_f32 v[8:9], v[32:33], v[38:39] neg_lo:[1,1] neg_hi:[1,1]
	s_nop 0
	v_add_f32_dpp v36, v18, v19 row_ror:8 row_mask:0xf bank_mask:0xf bound_ctrl:1
	ds_write_b32 v13, v36 offset:3328
	s_waitcnt lgkmcnt(9)
	v_pk_mul_f32 v[16:17], v[0:1], v[100:101]
	v_pk_mul_f32 v[18:19], v[4:5], v[100:101]
	v_pk_mul_f32 v[14:15], v[120:121], s[4:5] op_sel_hi:[1,0]
	v_pk_fma_f32 v[16:17], v[2:3], v[102:103], v[16:17]
	v_pk_fma_f32 v[18:19], v[6:7], v[102:103], v[18:19]
	v_pk_mul_f32 v[20:21], v[112:113], v[14:15] op_sel_hi:[1,0]
	v_pk_mul_f32 v[22:23], v[114:115], v[14:15] op_sel_hi:[1,0]
	v_add_f32_e32 v32, v16, v17
	v_add_f32_e32 v33, v18, v19
	v_pk_mul_f32 v[24:25], v[112:113], v[14:15] op_sel:[0,1] op_sel_hi:[1,1]
	v_pk_mul_f32 v[26:27], v[114:115], v[14:15] op_sel:[0,1] op_sel_hi:[1,1]
	v_cndmask_b32_e64 v34, v32, v33, s[6:7]
	v_cndmask_b32_e64 v35, v33, v32, s[6:7]
	v_pk_mul_f32 v[38:39], v[14:15], v[122:123] op_sel:[0,1] op_sel_hi:[1,1]
	v_pk_fma_f32 v[20:21], v[108:109], v[8:9], v[20:21] op_sel_hi:[1,0,1]
	v_add_f32_dpp v35, v34, v35 row_ror:8 row_mask:0xf bank_mask:0xf bound_ctrl:1
	v_pk_fma_f32 v[22:23], v[110:111], v[8:9], v[22:23] op_sel_hi:[1,0,1]
	v_pk_fma_f32 v[24:25], v[108:109], v[8:9], v[24:25] op_sel:[0,1,0] op_sel_hi:[1,1,1]
	v_pk_fma_f32 v[26:27], v[110:111], v[8:9], v[26:27] op_sel:[0,1,0] op_sel_hi:[1,1,1]
	v_add_f32_dpp v35, v35, v35 quad_perm:[1,0,3,2] row_mask:0xf bank_mask:0xf bound_ctrl:1
	v_pk_fma_f32 v[0:1], v[0:1], v[104:105], v[20:21]
	v_pk_fma_f32 v[2:3], v[2:3], v[106:107], v[22:23]
	v_pk_fma_f32 v[4:5], v[4:5], v[104:105], v[24:25]
	v_add_f32_dpp v35, v35, v35 quad_perm:[2,3,0,1] row_mask:0xf bank_mask:0xf bound_ctrl:1
	v_pk_fma_f32 v[6:7], v[6:7], v[106:107], v[26:27]
	v_pk_mul_f32 v[28:29], v[0:1], v[116:117]
	v_pk_fma_f32 v[38:39], v[8:9], v[122:123], v[38:39] op_sel_hi:[1,0,1]
	v_add_f32_dpp v35, v35, v35 row_half_mirror row_mask:0xf bank_mask:0xf bound_ctrl:1
	v_pk_mul_f32 v[30:31], v[4:5], v[116:117]
	v_pk_fma_f32 v[28:29], v[2:3], v[118:119], v[28:29]
	v_pk_fma_f32 v[30:31], v[6:7], v[118:119], v[30:31]
	v_mov_b32_dpp v34, v35 row_ror:8 row_mask:0xf bank_mask:0xf
	v_add_f32_e32 v16, v28, v29
	v_add_f32_e32 v17, v30, v31
	v_cndmask_b32_e64 v32, v34, v35, s[6:7]
	v_cndmask_b32_e64 v33, v35, v34, s[6:7]
	v_cndmask_b32_e64 v18, v16, v17, s[6:7]
	v_cndmask_b32_e64 v19, v17, v16, s[6:7]
	v_pk_add_f32 v[8:9], v[32:33], v[38:39] neg_lo:[1,1] neg_hi:[1,1]
	s_nop 0
	v_add_f32_dpp v36, v18, v19 row_ror:8 row_mask:0xf bank_mask:0xf bound_ctrl:1
	ds_write_b32 v13, v36 offset:3584
	s_waitcnt lgkmcnt(2)
	v_pk_mul_f32 v[16:17], v[0:1], v[52:53]
	v_pk_mul_f32 v[18:19], v[4:5], v[52:53]
	v_pk_mul_f32 v[14:15], v[72:73], s[4:5] op_sel_hi:[1,0]
	v_pk_fma_f32 v[16:17], v[2:3], v[54:55], v[16:17]
	v_pk_fma_f32 v[18:19], v[6:7], v[54:55], v[18:19]
	v_pk_mul_f32 v[20:21], v[64:65], v[14:15] op_sel_hi:[1,0]
	v_pk_mul_f32 v[22:23], v[66:67], v[14:15] op_sel_hi:[1,0]
	v_add_f32_e32 v32, v16, v17
	v_add_f32_e32 v33, v18, v19
	v_pk_mul_f32 v[24:25], v[64:65], v[14:15] op_sel:[0,1] op_sel_hi:[1,1]
	v_pk_mul_f32 v[26:27], v[66:67], v[14:15] op_sel:[0,1] op_sel_hi:[1,1]
	v_cndmask_b32_e64 v34, v32, v33, s[6:7]
	v_cndmask_b32_e64 v35, v33, v32, s[6:7]
	v_pk_mul_f32 v[38:39], v[14:15], v[74:75] op_sel:[0,1] op_sel_hi:[1,1]
	v_pk_fma_f32 v[20:21], v[60:61], v[8:9], v[20:21] op_sel_hi:[1,0,1]
	v_add_f32_dpp v35, v34, v35 row_ror:8 row_mask:0xf bank_mask:0xf bound_ctrl:1
	v_pk_fma_f32 v[22:23], v[62:63], v[8:9], v[22:23] op_sel_hi:[1,0,1]
	v_pk_fma_f32 v[24:25], v[60:61], v[8:9], v[24:25] op_sel:[0,1,0] op_sel_hi:[1,1,1]
	v_pk_fma_f32 v[26:27], v[62:63], v[8:9], v[26:27] op_sel:[0,1,0] op_sel_hi:[1,1,1]
	v_add_f32_dpp v35, v35, v35 quad_perm:[1,0,3,2] row_mask:0xf bank_mask:0xf bound_ctrl:1
	v_pk_fma_f32 v[0:1], v[0:1], v[56:57], v[20:21]
	v_pk_fma_f32 v[2:3], v[2:3], v[58:59], v[22:23]
	v_pk_fma_f32 v[4:5], v[4:5], v[56:57], v[24:25]
	v_add_f32_dpp v35, v35, v35 quad_perm:[2,3,0,1] row_mask:0xf bank_mask:0xf bound_ctrl:1
	v_pk_fma_f32 v[6:7], v[6:7], v[58:59], v[26:27]
	v_pk_mul_f32 v[28:29], v[0:1], v[68:69]
	v_pk_fma_f32 v[38:39], v[8:9], v[74:75], v[38:39] op_sel_hi:[1,0,1]
	v_add_f32_dpp v35, v35, v35 row_half_mirror row_mask:0xf bank_mask:0xf bound_ctrl:1
	v_pk_mul_f32 v[30:31], v[4:5], v[68:69]
	v_pk_fma_f32 v[28:29], v[2:3], v[70:71], v[28:29]
	v_pk_fma_f32 v[30:31], v[6:7], v[70:71], v[30:31]
	v_mov_b32_dpp v34, v35 row_ror:8 row_mask:0xf bank_mask:0xf
	v_add_f32_e32 v16, v28, v29
	v_add_f32_e32 v17, v30, v31
	v_cndmask_b32_e64 v32, v34, v35, s[6:7]
	v_cndmask_b32_e64 v33, v35, v34, s[6:7]
	v_cndmask_b32_e64 v18, v16, v17, s[6:7]
	v_cndmask_b32_e64 v19, v17, v16, s[6:7]
	v_pk_add_f32 v[8:9], v[32:33], v[38:39] neg_lo:[1,1] neg_hi:[1,1]
	s_nop 0
	v_add_f32_dpp v36, v18, v19 row_ror:8 row_mask:0xf bank_mask:0xf bound_ctrl:1
	ds_write_b32 v13, v36 offset:3840
	s_add_i32 s0, s0, 1
	s_waitcnt lgkmcnt(0)
	s_barrier
	s_cmpk_eq_i32 s0, 0x100
	s_cbranch_scc0 .Lsc_chunk
	s_setprio 0
	s_cmp_lg_u32 s14, 0
	s_cbranch_scc1 .LBB0_674
	v_readlane_b32 s0, v253, 16
	v_readlane_b32 s1, v253, 17
	s_nop 3
	s_add_u32 s0, s0, 0xec00000
	s_addc_u32 s1, s1, 0
	s_nop 3
	global_store_dwordx4 v49, v[0:3], s[0:1]
	global_store_dwordx4 v49, v[4:7], s[0:1] offset:256
